# retention tile loop: drop hipcc's conservative vmcnt from the S-phase Q-fragment waits (Q already drained by the explicit vmcnt(0)+barrier before the loop); they blocked on weight-conversion loads
# speedup vs baseline: 1.0013x; 1.0013x over previous
; #define LAS __attribute__((address_space(3)))
; #define RT_DMA_K(kt_, bf_, i_) __builtin_amdgcn_raw_ptr_buffer_load_lds(RK, (LAS void*)(lds + RT_K0 + (bf_) * 32768 + (w + 8 * (i_)) * 1024), 16, (int)RT_KOFF, (int)((unsigned)((b * SEQ + (kt_) * 64) * DR + h * 256) * 2u + (i_) * 65536u), 0, 0)
; #define RT_DMA_V(kt_, bf_, i_) __builtin_amdgcn_raw_ptr_buffer_load_lds(RV, (LAS void*)(lds + RT_V0 + (bf_) * 32768 + (w + 8 * (i_)) * 1024), 16, (int)RT_VOFF, (int)((unsigned)((h * 256) * MTOK + b * SEQ + (kt_) * 64) * 2u + (i_) * 1048576u), 0, 0)
; #define RT_KRD(dst, s0) do { _Pragma("unroll") for (int j_ = 0; j_ < 2; ++j_) dst[j_] = *(const LAS bf16x8*)(kb + ((((2 * ((s0) + j_)) | hh) ^ x15) << 4)); } while (0)
; #define RT_KMM(src, s0) do { _Pragma("unroll") for (int j_ = 0; j_ < 2; ++j_) st = __builtin_amdgcn_mfma_f32_32x32x16_bf16(src[j_], qf[(s0) + j_], st, 0, 0, 0); } while (0)
; __device__ __forceinline__ void p2_ret(const Frame& F, ArgsP a, int layer) {
;     ...
;                 { const LAS unsigned char* kb = lds + RT_K0 + bf * 32768 + (32 * wc + kap) * 512;
;     ...
;                   bf16x8 ka[2], kd[2], kc[2];
;                   RT_KRD(ka, 0); RT_KRD(kd, 2); __builtin_amdgcn_sched_barrier(0);
;                   RT_KRD(kc, 4); RT_KMM(ka, 0); if (pre) { RT_DMA_K(kt + 1, bf ^ 1, 0); RT_DMA_V(kt + 1, bf ^ 1, 0); } __builtin_amdgcn_sched_barrier(0);
;                   RT_KRD(ka, 6); RT_KMM(kd, 2); __builtin_amdgcn_sched_barrier(0);
;                   RT_KRD(kd, 8); RT_KMM(kc, 4); if (pre) { RT_DMA_K(kt + 1, bf ^ 1, 1); RT_DMA_V(kt + 1, bf ^ 1, 1); } __builtin_amdgcn_sched_barrier(0);
;                   RT_KRD(kc, 10); RT_KMM(ka, 6); __builtin_amdgcn_sched_barrier(0);
;                   RT_KRD(ka, 12); RT_KMM(kd, 8); if (pre) { RT_DMA_K(kt + 1, bf ^ 1, 2); RT_DMA_V(kt + 1, bf ^ 1, 2); } __builtin_amdgcn_sched_barrier(0);
;                   RT_KRD(kd, 14); RT_KMM(kc, 10); __builtin_amdgcn_sched_barrier(0);
;                   RT_KMM(ka, 12); if (pre) { RT_DMA_K(kt + 1, bf ^ 1, 3); RT_DMA_V(kt + 1, bf ^ 1, 3); } __builtin_amdgcn_sched_barrier(0);
;                   RT_KMM(kd, 14); __builtin_amdgcn_sched_barrier(0);
.LBB0_383:
	v_mov_b32_e32 v0, v207
	s_and_b32 s6, s31, 0x8000
	v_lshlrev_b32_e32 v99, 1, v0
	v_lshrrev_b32_e32 v100, 1, v0
	v_and_b32_e32 v98, 19, v0
	v_and_b32_e32 v99, 8, v99
	v_and_b32_e32 v100, 4, v100
	v_or3_b32 v115, v99, v98, v100
	v_ashrrev_i32_e32 v116, 5, v0
	s_add_i32 s4, s6, 0
	v_or_b32_e32 v98, s80, v115
	v_or_b32_e32 v99, 2, v116
	v_lshl_add_u32 v227, v98, 9, s4
	v_bitop3_b32 v98, v115, v116, 15 bitop3:0x6c
	v_bitop3_b32 v99, v115, v99, 15 bitop3:0x6c
	v_lshl_add_u32 v98, v98, 4, v227
	v_lshl_add_u32 v102, v99, 4, v227
	ds_read_b128 v[98:101], v98
	ds_read_b128 v[190:193], v102
	v_or_b32_e32 v102, 4, v116
	v_bitop3_b32 v102, v115, v102, 15 bitop3:0x6c
	v_or_b32_e32 v103, 6, v116
	v_lshl_add_u32 v102, v102, 4, v227
	v_bitop3_b32 v103, v115, v103, 15 bitop3:0x6c
	v_lshl_add_u32 v103, v103, 4, v227
	ds_read_b128 v[194:197], v102
	ds_read_b128 v[198:201], v103
	v_and_b32_e32 v117, 31, v0
	v_add_u32_e32 v216, s23, v116
	v_lshlrev_b32_e32 v217, 12, v216
	v_bitop3_b32 v216, v216, v117, 15 bitop3:0x6c
	v_or_b32_e32 v102, 8, v116
	s_xor_b32 s4, s6, 0x8000
	v_lshl_or_b32 v228, v216, 4, v217
	v_lshrrev_b32_e32 v217, 4, v0
	v_bitop3_b32 v102, v115, v102, 15 bitop3:0x6c
	v_or_b32_e32 v103, 10, v116
	s_add_i32 s5, s22, s4
	v_add_u32_e32 v217, s90, v217
	v_lshl_add_u32 v102, v102, 4, v227
	v_bitop3_b32 v103, v115, v103, 15 bitop3:0x6c
	s_add_i32 s7, s27, 0xfffd0000
	s_mov_b32 m0, s5
	v_lshrrev_b32_e32 v216, 3, v0
	v_xor_b32_e32 v217, v217, v0
	v_lshl_add_u32 v103, v103, 4, v227
	ds_read_b128 v[202:205], v102
	ds_read_b128 v[212:215], v103
	buffer_load_dwordx4 v228, s[40:43], s7 offen lds
	v_add_lshl_u32 v216, v216, s35, 14
	v_lshlrev_b32_e32 v217, 4, v217
	s_movk_i32 s7, 0x70
	v_and_or_b32 v229, v217, s7, v216
	s_add_i32 s7, s25, s30
	s_add_i32 m0, s33, s4
	s_add_i32 s12, s7, 0x80
	s_mov_b32 s46, s42
	s_mov_b32 s47, s43
	buffer_load_dwordx4 v229, s[44:47], s12 offen lds
	s_waitcnt lgkmcnt(5)
	v_mfma_f32_32x32x16_bf16 v[98:113], v[98:101], v[118:121], 0
	s_waitcnt lgkmcnt(4)
	v_mfma_f32_32x32x16_bf16 v[98:113], v[190:193], v[122:125], v[98:113]
	v_or_b32_e32 v190, 12, v116
	v_or_b32_e32 v191, 14, v116
	v_bitop3_b32 v190, v115, v190, 15 bitop3:0x6c
	v_bitop3_b32 v191, v115, v191, 15 bitop3:0x6c
	v_lshl_add_u32 v190, v190, 4, v227
	v_lshl_add_u32 v216, v191, 4, v227
	ds_read_b128 v[190:193], v190
	ds_read_b128 v[216:219], v216
	s_waitcnt lgkmcnt(5)
	v_mfma_f32_32x32x16_bf16 v[98:113], v[194:197], v[126:129], v[98:113]
	v_or_b32_e32 v194, 16, v116
	v_or_b32_e32 v195, 18, v116
	v_bitop3_b32 v194, v115, v194, 15 bitop3:0x6c
	v_bitop3_b32 v195, v115, v195, 15 bitop3:0x6c
	s_add_i32 s4, s4, 0
	v_lshl_add_u32 v194, v194, 4, v227
	s_add_i32 m0, s5, 0x2000
	s_waitcnt lgkmcnt(4)
	v_mfma_f32_32x32x16_bf16 v[98:113], v[198:201], v[130:133], v[98:113]
	v_lshl_add_u32 v198, v195, 4, v227
	s_add_i32 s12, s27, 0xfffe0000
	s_add_i32 s4, s4, 0x10000
	ds_read_b128 v[194:197], v194
	ds_read_b128 v[198:201], v198
	buffer_load_dwordx4 v228, s[40:43], s12 offen lds
	s_add_i32 m0, s4, s24
	s_add_i32 s12, s7, 0x100080
	buffer_load_dwordx4 v229, s[44:47], s12 offen lds
	s_waitcnt lgkmcnt(5)
	v_mfma_f32_32x32x16_bf16 v[98:113], v[202:205], v[134:137], v[98:113]
	s_waitcnt lgkmcnt(4)
	v_mfma_f32_32x32x16_bf16 v[98:113], v[212:215], v[138:141], v[98:113]
	v_or_b32_e32 v202, 20, v116
	v_or_b32_e32 v203, 22, v116
	v_bitop3_b32 v202, v115, v202, 15 bitop3:0x6c
	v_bitop3_b32 v203, v115, v203, 15 bitop3:0x6c
	v_lshl_add_u32 v202, v202, 4, v227
	v_lshl_add_u32 v212, v203, 4, v227
	ds_read_b128 v[202:205], v202
	ds_read_b128 v[212:215], v212
	s_waitcnt lgkmcnt(5)
	v_mfma_f32_32x32x16_bf16 v[98:113], v[190:193], v[142:145], v[98:113]
	v_or_b32_e32 v190, 24, v116
	v_or_b32_e32 v191, 26, v116
	v_bitop3_b32 v190, v115, v190, 15 bitop3:0x6c
	v_bitop3_b32 v191, v115, v191, 15 bitop3:0x6c
	v_lshl_add_u32 v190, v190, 4, v227
	s_add_i32 m0, s5, 0x4000
	s_add_i32 s12, s27, 0xffff0000
	s_waitcnt lgkmcnt(4)
	v_mfma_f32_32x32x16_bf16 v[98:113], v[216:219], v[146:149], v[98:113]
	v_lshl_add_u32 v216, v191, 4, v227
	ds_read_b128 v[190:193], v190
	ds_read_b128 v[216:219], v216
	buffer_load_dwordx4 v228, s[40:43], s12 offen lds
	s_add_i32 m0, s4, s26
	s_add_i32 s12, s7, 0x200080
	buffer_load_dwordx4 v229, s[44:47], s12 offen lds
	s_waitcnt lgkmcnt(5)
	v_mfma_f32_32x32x16_bf16 v[98:113], v[194:197], v[150:153], v[98:113]
	s_waitcnt lgkmcnt(4)
	v_mfma_f32_32x32x16_bf16 v[98:113], v[198:201], v[154:157], v[98:113]
	s_waitcnt lgkmcnt(3)
	v_mfma_f32_32x32x16_bf16 v[98:113], v[202:205], v[158:161], v[98:113]
	v_or_b32_e32 v194, 28, v116
	v_or_b32_e32 v195, 30, v116
	v_bitop3_b32 v194, v115, v194, 15 bitop3:0x6c
	v_bitop3_b32 v195, v115, v195, 15 bitop3:0x6c
	v_lshl_add_u32 v194, v194, 4, v227
	v_lshl_add_u32 v198, v195, 4, v227
	ds_read_b128 v[194:197], v194
	ds_read_b128 v[198:201], v198
	s_waitcnt lgkmcnt(4)
	v_mfma_f32_32x32x16_bf16 v[98:113], v[212:215], v[162:165], v[98:113]
	s_add_i32 m0, s5, 0x6000
	s_add_i32 s7, s7, 0x300080
	buffer_load_dwordx4 v228, s[40:43], s27 offen lds
	s_add_i32 m0, s4, s28
	s_waitcnt lgkmcnt(3)
	v_mfma_f32_32x32x16_bf16 v[98:113], v[190:193], v[166:169], v[98:113]
	buffer_load_dwordx4 v229, s[44:47], s7 offen lds
	s_waitcnt lgkmcnt(2)
	v_mfma_f32_32x32x16_bf16 v[98:113], v[216:219], v[170:173], v[98:113]
	s_waitcnt lgkmcnt(1)
	v_mfma_f32_32x32x16_bf16 v[98:113], v[194:197], v[174:177], v[98:113]
	s_waitcnt lgkmcnt(0)
	v_mfma_f32_32x32x16_bf16 v[98:113], v[198:201], v[178:181], v[98:113]
	s_cmp_ge_u32 s91, s29
	s_mov_b64 s[4:5], -1
	s_cbranch_scc0 .LBB0_385
; __device__ __forceinline__ unsigned cvt_pk_bf16(float lo, float hi) { unsigned r; asm volatile("v_cvt_pk_bf16_f32 %0, %1, %2" : "=v"(r) : "v"(lo), "v"(hi)); return r; }
; __device__ __forceinline__ void p2_ret(const Frame& F, ArgsP a, int layer) {
;     ...
;                 { const bool diag = kt >= 2 * qi;
;                   unsigned pk[8];
;                   if (!diag) { const float tf = __builtin_amdgcn_exp2f((float)(128 * (qi - (kt >> 1))) * lg2);
; #pragma unroll
;                       for (int i = 0; i < 8; ++i) pk[i] = cvt_pk_bf16(st[2 * i] * tf, st[2 * i + 1] * tf);
;                   } else { const int lim = wr * 32 + l31 + (2 * qi - kt) * 64 - 32 * wc - 8 * hh;
; #pragma unroll
;                       for (int i = 0; i < 8; ++i) { const int r0 = 2 * i, r1 = 2 * i + 1, o0 = 16 * (r0 >> 3) + (r0 & 7), o1 = 16 * (r1 >> 3) + (r1 & 7);
;                           pk[i] = cvt_pk_bf16((o0 <= lim) ? st[r0] : 0.f, (o1 <= lim) ? st[r1] : 0.f); } }
	v_lshlrev_b32_e32 v190, 3, v116
	v_sub_u32_e32 v117, v117, v190
	v_add_u32_e32 v117, s97, v117
	v_cmp_lt_i32_e32 vcc, -1, v117
	s_mov_b64 s[4:5], 0
	s_nop 3
	v_cndmask_b32_e32 v190, 0, v98, vcc
	v_cmp_lt_i32_e32 vcc, 0, v117
	s_nop 1
	v_cndmask_b32_e32 v191, 0, v99, vcc
	v_cmp_lt_i32_e32 vcc, 1, v117
	v_cvt_pk_bf16_f32 v190, v190, v191
	s_nop 1
	v_cndmask_b32_e32 v191, 0, v100, vcc
	v_cmp_lt_i32_e32 vcc, 2, v117
	s_nop 1
	v_cndmask_b32_e32 v192, 0, v101, vcc
	v_cmp_lt_i32_e32 vcc, 3, v117
	v_cvt_pk_bf16_f32 v191, v191, v192
	s_nop 1
	v_cndmask_b32_e32 v192, 0, v102, vcc
	v_cmp_lt_i32_e32 vcc, 4, v117
	s_nop 1
	v_cndmask_b32_e32 v193, 0, v103, vcc
	v_cmp_lt_i32_e32 vcc, 5, v117
	v_cvt_pk_bf16_f32 v192, v192, v193
	s_nop 1
	v_cndmask_b32_e32 v193, 0, v104, vcc
	v_cmp_lt_i32_e32 vcc, 6, v117
	s_nop 1
	v_cndmask_b32_e32 v194, 0, v105, vcc
	v_cmp_lt_i32_e32 vcc, 15, v117
	v_cvt_pk_bf16_f32 v193, v193, v194
	s_nop 1
	v_cndmask_b32_e32 v194, 0, v106, vcc
	v_cmp_lt_i32_e32 vcc, 16, v117
	s_nop 1
	v_cndmask_b32_e32 v195, 0, v107, vcc
	v_cmp_lt_i32_e32 vcc, 17, v117
	v_cvt_pk_bf16_f32 v194, v194, v195
	s_nop 1
	v_cndmask_b32_e32 v195, 0, v108, vcc
	v_cmp_lt_i32_e32 vcc, 18, v117
	s_nop 1
	v_cndmask_b32_e32 v196, 0, v109, vcc
	v_cmp_lt_i32_e32 vcc, 19, v117
	v_cvt_pk_bf16_f32 v195, v195, v196
	s_nop 1
	v_cndmask_b32_e32 v196, 0, v110, vcc
	v_cmp_lt_i32_e32 vcc, 20, v117
	s_nop 1
	v_cndmask_b32_e32 v197, 0, v111, vcc
	v_cmp_lt_i32_e32 vcc, 21, v117
	v_cvt_pk_bf16_f32 v196, v196, v197
	s_nop 1
	v_cndmask_b32_e32 v197, 0, v112, vcc
	v_cmp_lt_i32_e32 vcc, 22, v117
	s_nop 1
	v_cndmask_b32_e32 v117, 0, v113, vcc
	v_cvt_pk_bf16_f32 v197, v197, v117
